# additionally: residual-add GEMM epilogue software-pipelined (6 iterations of z loads in flight, scalar-base addressing)
# speedup vs baseline: 1.0312x; 1.0046x over previous
; DI const float* modp(const unsigned char* ws, int layer, int who, int idx) { return (const float*)(ws + WS_MOD) + ((size_t)(layer * 9 + who) * 6 + idx) * D; }
;     DI void operator()(const f32x4 (&acc)[2][2][4][2], const Unit& u, int wr, int wc, int fr, int fq) const {
;         const int b = u.pm / 17, jt = u.pm - b * 17;
;         const int who = jt == 0 ? 8 : b;
;         const float* gate = modp(ws, layer, who, gidx);
;         float* zb = jt == 0 ? (float*)(ws + WS_ZC) + (size_t)(b * LC) * D : out + (size_t)(b * SL + (jt - 1) * 256) * D;
;         const float* zs = jt == 0 ? zcs + (size_t)(b * LC) * D : zls + (size_t)(b * SL + (jt - 1) * 256) * D;
;         const int r0 = wr * 64 + fr, col0 = u.pn * 256 + wc * 32 + 8 * fq;
; #pragma unroll
;         for (int ai = 0; ai < 2; ++ai)
; #pragma unroll
;             for (int m = 0; m < 4; ++m)
; #pragma unroll
;                 for (int bj = 0; bj < 2; ++bj) {
;                     const int col = col0 + bj * 128;
;                     const f32x4 g0 = *(const f32x4*)(gate + col), g1 = *(const f32x4*)(gate + col + 4);
;                     const size_t zo = (size_t)(r0 + ai * 128 + m * 16) * D + col; float* zp = zb + zo; const float* zq = zs + zo;
;                     f32x4 z0 = *(const f32x4*)zq, z1 = *(const f32x4*)(zq + 4);
;                     z0 += g0 * acc[ai][bj][m][0]; z1 += g1 * acc[ai][bj][m][1];
;                     *(f32x4*)zp = z0; *(f32x4*)(zp + 4) = z1;
.LBB0_85:
	s_ashr_i32 s35, s34, 31
	s_lshl_b64 s[34:35], s[34:35], 12
	s_add_u32 s34, s2, s34
	s_addc_u32 s35, s3, s35
	s_ashr_i32 s39, s38, 31
	s_lshl_b64 s[2:3], s[38:39], 12
	s_add_u32 s38, s36, s2
	v_readlane_b32 s2, v255, 31
	s_mul_i32 s2, s2, 9
	s_addc_u32 s39, s37, s3
	s_add_i32 s2, s21, s2
	s_mul_i32 s2, s2, 6
	s_ashr_i32 s3, s2, 31
	s_lshl_b64 s[2:3], s[2:3], 12
	v_lshl_or_b32 v164, s72, 8, v166
	s_add_u32 s2, s69, s2
	v_ashrrev_i32_e32 v165, 31, v164
	s_addc_u32 s3, s70, s3
	v_lshlrev_b32_e32 v162, 2, v164
	global_load_dwordx4 v[198:201], v162, s[2:3]
	global_load_dwordx4 v[202:205], v162, s[2:3] offset:16
	global_load_dwordx4 v[206:209], v162, s[2:3] offset:512
	global_load_dwordx4 v[210:213], v162, s[2:3] offset:528
	v_add_lshl_u32 v163, v136, v164, 2
	global_load_dwordx4 v[214:217], v163, s[38:39]
	global_load_dwordx4 v[218:221], v163, s[38:39] offset:16
	global_load_dwordx4 v[222:225], v163, s[38:39] offset:512
	global_load_dwordx4 v[226:229], v163, s[38:39] offset:528
	v_add_lshl_u32 v180, v144, v164, 2
	global_load_dwordx4 v[230:233], v180, s[38:39]
	global_load_dwordx4 v[188:191], v180, s[38:39] offset:16
	global_load_dwordx4 v[192:195], v180, s[38:39] offset:512
	global_load_dwordx4 v[140:143], v180, s[38:39] offset:528
	v_add_lshl_u32 v181, v146, v164, 2
	global_load_dwordx4 v[168:171], v181, s[38:39]
	global_load_dwordx4 v[172:175], v181, s[38:39] offset:16
	global_load_dwordx4 v[176:179], v181, s[38:39] offset:512
	global_load_dwordx4 v[244:247], v181, s[38:39] offset:528
	s_waitcnt vmcnt(10)
	v_pk_fma_f32 v[128:129], v[128:129], v[200:201], v[216:217]
	v_pk_fma_f32 v[126:127], v[126:127], v[198:199], v[214:215]
	v_pk_fma_f32 v[124:125], v[124:125], v[204:205], v[220:221]
	v_pk_fma_f32 v[122:123], v[122:123], v[202:203], v[218:219]
	global_store_dwordx4 v163, v[126:129], s[34:35]
	global_store_dwordx4 v163, v[122:125], s[34:35] offset:16
	v_add_lshl_u32 v234, v148, v164, 2
	global_load_dwordx4 v[214:217], v234, s[38:39]
	global_load_dwordx4 v[218:221], v234, s[38:39] offset:16
	s_waitcnt vmcnt(12)
	v_pk_fma_f32 v[120:121], v[120:121], v[208:209], v[224:225]
	v_pk_fma_f32 v[118:119], v[118:119], v[206:207], v[222:223]
	v_pk_fma_f32 v[116:117], v[116:117], v[212:213], v[228:229]
	v_pk_fma_f32 v[114:115], v[114:115], v[210:211], v[226:227]
	global_store_dwordx4 v163, v[118:121], s[34:35] offset:512
	global_store_dwordx4 v163, v[114:117], s[34:35] offset:528
	global_load_dwordx4 v[222:225], v234, s[38:39] offset:512
	global_load_dwordx4 v[226:229], v234, s[38:39] offset:528
	s_waitcnt vmcnt(14)
	v_pk_fma_f32 v[112:113], v[112:113], v[200:201], v[232:233]
	v_pk_fma_f32 v[110:111], v[110:111], v[198:199], v[230:231]
	v_pk_fma_f32 v[108:109], v[108:109], v[204:205], v[190:191]
	v_pk_fma_f32 v[106:107], v[106:107], v[202:203], v[188:189]
	global_store_dwordx4 v180, v[110:113], s[34:35]
	global_store_dwordx4 v180, v[106:109], s[34:35] offset:16
	v_add_lshl_u32 v163, v150, v164, 2
	global_load_dwordx4 v[230:233], v163, s[38:39]
	global_load_dwordx4 v[188:191], v163, s[38:39] offset:16
	s_waitcnt vmcnt(16)
	v_pk_fma_f32 v[104:105], v[104:105], v[208:209], v[194:195]
	v_pk_fma_f32 v[102:103], v[102:103], v[206:207], v[192:193]
	v_pk_fma_f32 v[100:101], v[100:101], v[212:213], v[142:143]
	v_pk_fma_f32 v[98:99], v[98:99], v[210:211], v[140:141]
	global_store_dwordx4 v180, v[102:105], s[34:35] offset:512
	global_store_dwordx4 v180, v[98:101], s[34:35] offset:528
	global_load_dwordx4 v[192:195], v163, s[38:39] offset:512
	global_load_dwordx4 v[140:143], v163, s[38:39] offset:528
	s_waitcnt vmcnt(18)
	v_pk_fma_f32 v[96:97], v[96:97], v[200:201], v[170:171]
	v_pk_fma_f32 v[94:95], v[94:95], v[198:199], v[168:169]
	v_pk_fma_f32 v[92:93], v[92:93], v[204:205], v[174:175]
	v_pk_fma_f32 v[90:91], v[90:91], v[202:203], v[172:173]
	global_store_dwordx4 v181, v[94:97], s[34:35]
	global_store_dwordx4 v181, v[90:93], s[34:35] offset:16
	v_add_lshl_u32 v180, v152, v164, 2
	global_load_dwordx4 v[168:171], v180, s[38:39]
	global_load_dwordx4 v[172:175], v180, s[38:39] offset:16
	s_waitcnt vmcnt(20)
	v_pk_fma_f32 v[88:89], v[88:89], v[208:209], v[178:179]
	v_pk_fma_f32 v[86:87], v[86:87], v[206:207], v[176:177]
	v_pk_fma_f32 v[84:85], v[84:85], v[212:213], v[246:247]
	v_pk_fma_f32 v[82:83], v[82:83], v[210:211], v[244:245]
	global_store_dwordx4 v181, v[86:89], s[34:35] offset:512
	global_store_dwordx4 v181, v[82:85], s[34:35] offset:528
	global_load_dwordx4 v[176:179], v180, s[38:39] offset:512
	global_load_dwordx4 v[244:247], v180, s[38:39] offset:528
	s_waitcnt vmcnt(20)
; #define PG8_BAR __builtin_amdgcn_s_barrier()
; template <class AF, class Epi>
; DI void gemm_phase(LAS unsigned char* lds, const AF& af, const bf16_t* Bt, int lda, int K, const StaticOrder& S, const Epi& E) {
;     ...
;         if (!has_next) break;
; #pragma unroll
;         for (int a = 0; a < 2; ++a)
; #pragma unroll
;             for (int b = 0; b < 2; ++b)
; #pragma unroll
;                 for (int m = 0; m < 4; ++m)
; #pragma unroll
;                     for (int n = 0; n < 2; ++n) acc[a][b][m][n] = (f32x4){0.f, 0.f, 0.f, 0.f};
;         cur = nxt; cA = nA; cB = nB; ++ui;
;         if (wr == 1) PG8_BAR;
;     DI void operator()(const f32x4 (&acc)[2][2][4][2], const Unit& u, int wr, int wc, int fr, int fq) const {
;     ...
;         for (int ai = 0; ai < 2; ++ai)
; #pragma unroll
;             for (int m = 0; m < 4; ++m)
; #pragma unroll
;                 for (int bj = 0; bj < 2; ++bj) {
;                     const int col = col0 + bj * 128;
;                     const f32x4 g0 = *(const f32x4*)(gate + col), g1 = *(const f32x4*)(gate + col + 4);
;                     const size_t zo = (size_t)(r0 + ai * 128 + m * 16) * D + col; float* zp = zb + zo; const float* zq = zs + zo;
;                     f32x4 z0 = *(const f32x4*)zq, z1 = *(const f32x4*)(zq + 4);
;                     z0 += g0 * acc[ai][bj][m][0]; z1 += g1 * acc[ai][bj][m][1];
;                     *(f32x4*)zp = z0; *(f32x4*)(zp + 4) = z1;
;                     __builtin_amdgcn_sched_barrier(0);
;                 }
	v_pk_fma_f32 v[80:81], v[80:81], v[200:201], v[216:217]
	v_pk_fma_f32 v[78:79], v[78:79], v[198:199], v[214:215]
	v_pk_fma_f32 v[76:77], v[76:77], v[204:205], v[220:221]
	v_pk_fma_f32 v[74:75], v[74:75], v[202:203], v[218:219]
	global_store_dwordx4 v234, v[78:81], s[34:35]
	global_store_dwordx4 v234, v[74:77], s[34:35] offset:16
	v_add_lshl_u32 v181, v154, v164, 2
	global_load_dwordx4 v[214:217], v181, s[38:39]
	global_load_dwordx4 v[218:221], v181, s[38:39] offset:16
	s_waitcnt vmcnt(20)
	v_pk_fma_f32 v[72:73], v[72:73], v[208:209], v[224:225]
	v_pk_fma_f32 v[70:71], v[70:71], v[206:207], v[222:223]
	v_pk_fma_f32 v[68:69], v[68:69], v[212:213], v[228:229]
	v_pk_fma_f32 v[66:67], v[66:67], v[210:211], v[226:227]
	global_store_dwordx4 v234, v[70:73], s[34:35] offset:512
	global_store_dwordx4 v234, v[66:69], s[34:35] offset:528
	global_load_dwordx4 v[222:225], v181, s[38:39] offset:512
	global_load_dwordx4 v[226:229], v181, s[38:39] offset:528
	s_waitcnt vmcnt(20)
	v_pk_fma_f32 v[64:65], v[64:65], v[200:201], v[232:233]
	v_pk_fma_f32 v[62:63], v[62:63], v[198:199], v[230:231]
	v_pk_fma_f32 v[60:61], v[60:61], v[204:205], v[190:191]
	v_pk_fma_f32 v[58:59], v[58:59], v[202:203], v[188:189]
	global_store_dwordx4 v163, v[62:65], s[34:35]
	global_store_dwordx4 v163, v[58:61], s[34:35] offset:16
	v_add_lshl_u32 v234, v156, v164, 2
	global_load_dwordx4 v[230:233], v234, s[38:39]
	global_load_dwordx4 v[188:191], v234, s[38:39] offset:16
	s_waitcnt vmcnt(20)
	v_pk_fma_f32 v[56:57], v[56:57], v[208:209], v[194:195]
	v_pk_fma_f32 v[54:55], v[54:55], v[206:207], v[192:193]
	v_pk_fma_f32 v[52:53], v[52:53], v[212:213], v[142:143]
	v_pk_fma_f32 v[50:51], v[50:51], v[210:211], v[140:141]
	global_store_dwordx4 v163, v[54:57], s[34:35] offset:512
	global_store_dwordx4 v163, v[50:53], s[34:35] offset:528
	global_load_dwordx4 v[192:195], v234, s[38:39] offset:512
	global_load_dwordx4 v[140:143], v234, s[38:39] offset:528
	s_waitcnt vmcnt(20)
	v_pk_fma_f32 v[48:49], v[48:49], v[200:201], v[170:171]
	v_pk_fma_f32 v[46:47], v[46:47], v[198:199], v[168:169]
	v_pk_fma_f32 v[44:45], v[44:45], v[204:205], v[174:175]
	v_pk_fma_f32 v[42:43], v[42:43], v[202:203], v[172:173]
	global_store_dwordx4 v180, v[46:49], s[34:35]
	global_store_dwordx4 v180, v[42:45], s[34:35] offset:16
	s_waitcnt vmcnt(18)
	v_pk_fma_f32 v[40:41], v[40:41], v[208:209], v[178:179]
	v_pk_fma_f32 v[38:39], v[38:39], v[206:207], v[176:177]
	v_pk_fma_f32 v[36:37], v[36:37], v[212:213], v[246:247]
	v_pk_fma_f32 v[34:35], v[34:35], v[210:211], v[244:245]
	global_store_dwordx4 v180, v[38:41], s[34:35] offset:512
	global_store_dwordx4 v180, v[34:37], s[34:35] offset:528
	s_waitcnt vmcnt(16)
	v_pk_fma_f32 v[32:33], v[32:33], v[200:201], v[216:217]
	v_pk_fma_f32 v[30:31], v[30:31], v[198:199], v[214:215]
	v_pk_fma_f32 v[28:29], v[28:29], v[204:205], v[220:221]
	v_pk_fma_f32 v[26:27], v[26:27], v[202:203], v[218:219]
	global_store_dwordx4 v181, v[30:33], s[34:35]
	global_store_dwordx4 v181, v[26:29], s[34:35] offset:16
	s_waitcnt vmcnt(14)
	v_pk_fma_f32 v[24:25], v[24:25], v[208:209], v[224:225]
	v_pk_fma_f32 v[22:23], v[22:23], v[206:207], v[222:223]
	v_pk_fma_f32 v[20:21], v[20:21], v[212:213], v[228:229]
	v_pk_fma_f32 v[18:19], v[18:19], v[210:211], v[226:227]
	global_store_dwordx4 v181, v[22:25], s[34:35] offset:512
	global_store_dwordx4 v181, v[18:21], s[34:35] offset:528
	s_waitcnt vmcnt(12)
	v_pk_fma_f32 v[16:17], v[16:17], v[200:201], v[232:233]
	v_pk_fma_f32 v[14:15], v[14:15], v[198:199], v[230:231]
	v_pk_fma_f32 v[12:13], v[12:13], v[204:205], v[190:191]
	v_pk_fma_f32 v[10:11], v[10:11], v[202:203], v[188:189]
	global_store_dwordx4 v234, v[14:17], s[34:35]
	global_store_dwordx4 v234, v[10:13], s[34:35] offset:16
	s_waitcnt vmcnt(10)
	v_pk_fma_f32 v[8:9], v[8:9], v[208:209], v[194:195]
	v_pk_fma_f32 v[6:7], v[6:7], v[206:207], v[192:193]
	v_pk_fma_f32 v[4:5], v[4:5], v[212:213], v[142:143]
	v_pk_fma_f32 v[2:3], v[2:3], v[210:211], v[140:141]
	global_store_dwordx4 v234, v[6:9], s[34:35] offset:512
	global_store_dwordx4 v234, v[2:5], s[34:35] offset:528
	s_andn2_b64 vcc, exec, s[6:7]
	s_mov_b64 s[2:3], -1
	s_cbranch_vccnz .LBB0_71
	s_andn2_b64 vcc, exec, s[16:17]
	s_cbranch_vccnz .LBB0_70
	s_barrier
	s_branch .LBB0_70

; DI const float* modp(const unsigned char* ws, int layer, int who, int idx) { return (const float*)(ws + WS_MOD) + ((size_t)(layer * 9 + who) * 6 + idx) * D; }
;     DI void operator()(const f32x4 (&acc)[2][2][4][2], const Unit& u, int wr, int wc, int fr, int fq) const {
;         const int b = u.pm / 17, jt = u.pm - b * 17;
;         const int who = jt == 0 ? 8 : b;
;         const float* gate = modp(ws, layer, who, gidx);
;         float* zb = jt == 0 ? (float*)(ws + WS_ZC) + (size_t)(b * LC) * D : out + (size_t)(b * SL + (jt - 1) * 256) * D;
;         const float* zs = jt == 0 ? zcs + (size_t)(b * LC) * D : zls + (size_t)(b * SL + (jt - 1) * 256) * D;
;         const int r0 = wr * 64 + fr, col0 = u.pn * 256 + wc * 32 + 8 * fq;
; #pragma unroll
;         for (int ai = 0; ai < 2; ++ai)
; #pragma unroll
;             for (int m = 0; m < 4; ++m)
; #pragma unroll
;                 for (int bj = 0; bj < 2; ++bj) {
;                     const int col = col0 + bj * 128;
;                     const f32x4 g0 = *(const f32x4*)(gate + col), g1 = *(const f32x4*)(gate + col + 4);
;                     const size_t zo = (size_t)(r0 + ai * 128 + m * 16) * D + col; float* zp = zb + zo; const float* zq = zs + zo;
;                     f32x4 z0 = *(const f32x4*)zq, z1 = *(const f32x4*)(zq + 4);
;                     z0 += g0 * acc[ai][bj][m][0]; z1 += g1 * acc[ai][bj][m][1];
;                     *(f32x4*)zp = z0; *(f32x4*)(zp + 4) = z1;
.LBB0_497:
	s_ashr_i32 s7, s6, 31
	s_lshl_b64 s[6:7], s[6:7], 12
	s_add_u32 s6, s2, s6
	s_addc_u32 s7, s3, s7
	s_ashr_i32 s29, s28, 31
	s_lshl_b64 s[2:3], s[28:29], 12
	s_add_u32 s28, s34, s2
	v_readlane_b32 s2, v255, 31
	s_mul_i32 s2, s2, 9
	s_addc_u32 s29, s35, s3
	s_add_i32 s2, s21, s2
	s_mul_i32 s2, s2, 6
	s_ashr_i32 s3, s2, 31
	s_lshl_b64 s[2:3], s[2:3], 12
	v_lshl_or_b32 v164, s66, 8, v166
	s_add_u32 s2, s62, s2
	v_ashrrev_i32_e32 v165, 31, v164
	s_addc_u32 s3, s63, s3
	v_lshlrev_b32_e32 v162, 2, v164
	global_load_dwordx4 v[198:201], v162, s[2:3]
	global_load_dwordx4 v[202:205], v162, s[2:3] offset:16
	global_load_dwordx4 v[206:209], v162, s[2:3] offset:512
	global_load_dwordx4 v[210:213], v162, s[2:3] offset:528
	v_add_lshl_u32 v163, v136, v164, 2
	global_load_dwordx4 v[214:217], v163, s[28:29]
	global_load_dwordx4 v[218:221], v163, s[28:29] offset:16
	global_load_dwordx4 v[222:225], v163, s[28:29] offset:512
	global_load_dwordx4 v[226:229], v163, s[28:29] offset:528
	v_add_lshl_u32 v180, v144, v164, 2
	global_load_dwordx4 v[230:233], v180, s[28:29]
	global_load_dwordx4 v[188:191], v180, s[28:29] offset:16
	global_load_dwordx4 v[192:195], v180, s[28:29] offset:512
	global_load_dwordx4 v[140:143], v180, s[28:29] offset:528
	v_add_lshl_u32 v181, v146, v164, 2
	global_load_dwordx4 v[168:171], v181, s[28:29]
	global_load_dwordx4 v[172:175], v181, s[28:29] offset:16
	global_load_dwordx4 v[176:179], v181, s[28:29] offset:512
	global_load_dwordx4 v[244:247], v181, s[28:29] offset:528
	s_waitcnt vmcnt(10)
	v_pk_fma_f32 v[128:129], v[128:129], v[200:201], v[216:217]
	v_pk_fma_f32 v[126:127], v[126:127], v[198:199], v[214:215]
	v_pk_fma_f32 v[124:125], v[124:125], v[204:205], v[220:221]
	v_pk_fma_f32 v[122:123], v[122:123], v[202:203], v[218:219]
	global_store_dwordx4 v163, v[126:129], s[6:7]
	global_store_dwordx4 v163, v[122:125], s[6:7] offset:16
	v_add_lshl_u32 v234, v148, v164, 2
	global_load_dwordx4 v[214:217], v234, s[28:29]
	global_load_dwordx4 v[218:221], v234, s[28:29] offset:16
	s_waitcnt vmcnt(12)
	v_pk_fma_f32 v[120:121], v[120:121], v[208:209], v[224:225]
	v_pk_fma_f32 v[118:119], v[118:119], v[206:207], v[222:223]
	v_pk_fma_f32 v[116:117], v[116:117], v[212:213], v[228:229]
	v_pk_fma_f32 v[114:115], v[114:115], v[210:211], v[226:227]
	global_store_dwordx4 v163, v[118:121], s[6:7] offset:512
	global_store_dwordx4 v163, v[114:117], s[6:7] offset:528
	global_load_dwordx4 v[222:225], v234, s[28:29] offset:512
	global_load_dwordx4 v[226:229], v234, s[28:29] offset:528
	s_waitcnt vmcnt(14)
	v_pk_fma_f32 v[112:113], v[112:113], v[200:201], v[232:233]
	v_pk_fma_f32 v[110:111], v[110:111], v[198:199], v[230:231]
	v_pk_fma_f32 v[108:109], v[108:109], v[204:205], v[190:191]
	v_pk_fma_f32 v[106:107], v[106:107], v[202:203], v[188:189]
	global_store_dwordx4 v180, v[110:113], s[6:7]
	global_store_dwordx4 v180, v[106:109], s[6:7] offset:16
	v_add_lshl_u32 v163, v150, v164, 2
	global_load_dwordx4 v[230:233], v163, s[28:29]
	global_load_dwordx4 v[188:191], v163, s[28:29] offset:16
	s_waitcnt vmcnt(16)
	v_pk_fma_f32 v[104:105], v[104:105], v[208:209], v[194:195]
	v_pk_fma_f32 v[102:103], v[102:103], v[206:207], v[192:193]
	v_pk_fma_f32 v[100:101], v[100:101], v[212:213], v[142:143]
	v_pk_fma_f32 v[98:99], v[98:99], v[210:211], v[140:141]
	global_store_dwordx4 v180, v[102:105], s[6:7] offset:512
	global_store_dwordx4 v180, v[98:101], s[6:7] offset:528
	global_load_dwordx4 v[192:195], v163, s[28:29] offset:512
	global_load_dwordx4 v[140:143], v163, s[28:29] offset:528
	s_waitcnt vmcnt(18)
	v_pk_fma_f32 v[96:97], v[96:97], v[200:201], v[170:171]
	v_pk_fma_f32 v[94:95], v[94:95], v[198:199], v[168:169]
	v_pk_fma_f32 v[92:93], v[92:93], v[204:205], v[174:175]
	v_pk_fma_f32 v[90:91], v[90:91], v[202:203], v[172:173]
	global_store_dwordx4 v181, v[94:97], s[6:7]
	global_store_dwordx4 v181, v[90:93], s[6:7] offset:16
	v_add_lshl_u32 v180, v152, v164, 2
	global_load_dwordx4 v[168:171], v180, s[28:29]
	global_load_dwordx4 v[172:175], v180, s[28:29] offset:16
	s_waitcnt vmcnt(20)
	v_pk_fma_f32 v[88:89], v[88:89], v[208:209], v[178:179]
	v_pk_fma_f32 v[86:87], v[86:87], v[206:207], v[176:177]
	v_pk_fma_f32 v[84:85], v[84:85], v[212:213], v[246:247]
	v_pk_fma_f32 v[82:83], v[82:83], v[210:211], v[244:245]
	global_store_dwordx4 v181, v[86:89], s[6:7] offset:512
	global_store_dwordx4 v181, v[82:85], s[6:7] offset:528
	global_load_dwordx4 v[176:179], v180, s[28:29] offset:512
	global_load_dwordx4 v[244:247], v180, s[28:29] offset:528
	s_waitcnt vmcnt(20)
; #define PG8_BAR __builtin_amdgcn_s_barrier()
; template <class AF, class Epi>
; DI void gemm_phase(LAS unsigned char* lds, const AF& af, const bf16_t* Bt, int lda, int K, const StaticOrder& S, const Epi& E) {
;     ...
;         if (!has_next) break;
; #pragma unroll
;         for (int a = 0; a < 2; ++a)
; #pragma unroll
;             for (int b = 0; b < 2; ++b)
; #pragma unroll
;                 for (int m = 0; m < 4; ++m)
; #pragma unroll
;                     for (int n = 0; n < 2; ++n) acc[a][b][m][n] = (f32x4){0.f, 0.f, 0.f, 0.f};
;         cur = nxt; cA = nA; cB = nB; ++ui;
;         if (wr == 1) PG8_BAR;
;     DI void operator()(const f32x4 (&acc)[2][2][4][2], const Unit& u, int wr, int wc, int fr, int fq) const {
;     ...
;         for (int ai = 0; ai < 2; ++ai)
; #pragma unroll
;             for (int m = 0; m < 4; ++m)
; #pragma unroll
;                 for (int bj = 0; bj < 2; ++bj) {
;                     const int col = col0 + bj * 128;
;                     const f32x4 g0 = *(const f32x4*)(gate + col), g1 = *(const f32x4*)(gate + col + 4);
;                     const size_t zo = (size_t)(r0 + ai * 128 + m * 16) * D + col; float* zp = zb + zo; const float* zq = zs + zo;
;                     f32x4 z0 = *(const f32x4*)zq, z1 = *(const f32x4*)(zq + 4);
;                     z0 += g0 * acc[ai][bj][m][0]; z1 += g1 * acc[ai][bj][m][1];
;                     *(f32x4*)zp = z0; *(f32x4*)(zp + 4) = z1;
;                     __builtin_amdgcn_sched_barrier(0);
;                 }
	v_pk_fma_f32 v[80:81], v[80:81], v[200:201], v[216:217]
	v_pk_fma_f32 v[78:79], v[78:79], v[198:199], v[214:215]
	v_pk_fma_f32 v[76:77], v[76:77], v[204:205], v[220:221]
	v_pk_fma_f32 v[74:75], v[74:75], v[202:203], v[218:219]
	global_store_dwordx4 v234, v[78:81], s[6:7]
	global_store_dwordx4 v234, v[74:77], s[6:7] offset:16
	v_add_lshl_u32 v181, v154, v164, 2
	global_load_dwordx4 v[214:217], v181, s[28:29]
	global_load_dwordx4 v[218:221], v181, s[28:29] offset:16
	s_waitcnt vmcnt(20)
	v_pk_fma_f32 v[72:73], v[72:73], v[208:209], v[224:225]
	v_pk_fma_f32 v[70:71], v[70:71], v[206:207], v[222:223]
	v_pk_fma_f32 v[68:69], v[68:69], v[212:213], v[228:229]
	v_pk_fma_f32 v[66:67], v[66:67], v[210:211], v[226:227]
	global_store_dwordx4 v234, v[70:73], s[6:7] offset:512
	global_store_dwordx4 v234, v[66:69], s[6:7] offset:528
	global_load_dwordx4 v[222:225], v181, s[28:29] offset:512
	global_load_dwordx4 v[226:229], v181, s[28:29] offset:528
	s_waitcnt vmcnt(20)
	v_pk_fma_f32 v[64:65], v[64:65], v[200:201], v[232:233]
	v_pk_fma_f32 v[62:63], v[62:63], v[198:199], v[230:231]
	v_pk_fma_f32 v[60:61], v[60:61], v[204:205], v[190:191]
	v_pk_fma_f32 v[58:59], v[58:59], v[202:203], v[188:189]
	global_store_dwordx4 v163, v[62:65], s[6:7]
	global_store_dwordx4 v163, v[58:61], s[6:7] offset:16
	v_add_lshl_u32 v234, v156, v164, 2
	global_load_dwordx4 v[230:233], v234, s[28:29]
	global_load_dwordx4 v[188:191], v234, s[28:29] offset:16
	s_waitcnt vmcnt(20)
	v_pk_fma_f32 v[56:57], v[56:57], v[208:209], v[194:195]
	v_pk_fma_f32 v[54:55], v[54:55], v[206:207], v[192:193]
	v_pk_fma_f32 v[52:53], v[52:53], v[212:213], v[142:143]
	v_pk_fma_f32 v[50:51], v[50:51], v[210:211], v[140:141]
	global_store_dwordx4 v163, v[54:57], s[6:7] offset:512
	global_store_dwordx4 v163, v[50:53], s[6:7] offset:528
	global_load_dwordx4 v[192:195], v234, s[28:29] offset:512
	global_load_dwordx4 v[140:143], v234, s[28:29] offset:528
	s_waitcnt vmcnt(20)
	v_pk_fma_f32 v[48:49], v[48:49], v[200:201], v[170:171]
	v_pk_fma_f32 v[46:47], v[46:47], v[198:199], v[168:169]
	v_pk_fma_f32 v[44:45], v[44:45], v[204:205], v[174:175]
	v_pk_fma_f32 v[42:43], v[42:43], v[202:203], v[172:173]
	global_store_dwordx4 v180, v[46:49], s[6:7]
	global_store_dwordx4 v180, v[42:45], s[6:7] offset:16
	s_waitcnt vmcnt(18)
	v_pk_fma_f32 v[40:41], v[40:41], v[208:209], v[178:179]
	v_pk_fma_f32 v[38:39], v[38:39], v[206:207], v[176:177]
	v_pk_fma_f32 v[36:37], v[36:37], v[212:213], v[246:247]
	v_pk_fma_f32 v[34:35], v[34:35], v[210:211], v[244:245]
	global_store_dwordx4 v180, v[38:41], s[6:7] offset:512
	global_store_dwordx4 v180, v[34:37], s[6:7] offset:528
	s_waitcnt vmcnt(16)
	v_pk_fma_f32 v[32:33], v[32:33], v[200:201], v[216:217]
	v_pk_fma_f32 v[30:31], v[30:31], v[198:199], v[214:215]
	v_pk_fma_f32 v[28:29], v[28:29], v[204:205], v[220:221]
	v_pk_fma_f32 v[26:27], v[26:27], v[202:203], v[218:219]
	global_store_dwordx4 v181, v[30:33], s[6:7]
	global_store_dwordx4 v181, v[26:29], s[6:7] offset:16
	s_waitcnt vmcnt(14)
	v_pk_fma_f32 v[24:25], v[24:25], v[208:209], v[224:225]
	v_pk_fma_f32 v[22:23], v[22:23], v[206:207], v[222:223]
	v_pk_fma_f32 v[20:21], v[20:21], v[212:213], v[228:229]
	v_pk_fma_f32 v[18:19], v[18:19], v[210:211], v[226:227]
	global_store_dwordx4 v181, v[22:25], s[6:7] offset:512
	global_store_dwordx4 v181, v[18:21], s[6:7] offset:528
	s_waitcnt vmcnt(12)
	v_pk_fma_f32 v[16:17], v[16:17], v[200:201], v[232:233]
	v_pk_fma_f32 v[14:15], v[14:15], v[198:199], v[230:231]
	v_pk_fma_f32 v[12:13], v[12:13], v[204:205], v[190:191]
	v_pk_fma_f32 v[10:11], v[10:11], v[202:203], v[188:189]
	global_store_dwordx4 v234, v[14:17], s[6:7]
	global_store_dwordx4 v234, v[10:13], s[6:7] offset:16
	s_waitcnt vmcnt(10)
	v_pk_fma_f32 v[8:9], v[8:9], v[208:209], v[194:195]
	v_pk_fma_f32 v[6:7], v[6:7], v[206:207], v[192:193]
	v_pk_fma_f32 v[4:5], v[4:5], v[212:213], v[142:143]
	v_pk_fma_f32 v[2:3], v[2:3], v[210:211], v[140:141]
	global_store_dwordx4 v234, v[6:9], s[6:7] offset:512
	global_store_dwordx4 v234, v[2:5], s[6:7] offset:528
	s_and_b64 vcc, exec, s[4:5]
	s_mov_b64 s[2:3], -1
	s_cbranch_vccnz .LBB0_482
	s_andn2_b64 vcc, exec, s[16:17]
	s_cbranch_vccnz .LBB0_481
	s_barrier
	s_branch .LBB0_481

; DI const float* modp(const unsigned char* ws, int layer, int who, int idx) { return (const float*)(ws + WS_MOD) + ((size_t)(layer * 9 + who) * 6 + idx) * D; }
;     DI void operator()(const f32x4 (&acc)[2][2][4][2], const Unit& u, int wr, int wc, int fr, int fq) const {
;         const int b = u.pm / 17, jt = u.pm - b * 17;
;         const int who = jt == 0 ? 8 : b;
;         const float* gate = modp(ws, layer, who, gidx);
;         float* zb = jt == 0 ? (float*)(ws + WS_ZC) + (size_t)(b * LC) * D : out + (size_t)(b * SL + (jt - 1) * 256) * D;
;         const float* zs = jt == 0 ? zcs + (size_t)(b * LC) * D : zls + (size_t)(b * SL + (jt - 1) * 256) * D;
;         const int r0 = wr * 64 + fr, col0 = u.pn * 256 + wc * 32 + 8 * fq;
; #pragma unroll
;         for (int ai = 0; ai < 2; ++ai)
; #pragma unroll
;             for (int m = 0; m < 4; ++m)
; #pragma unroll
;                 for (int bj = 0; bj < 2; ++bj) {
;                     const int col = col0 + bj * 128;
;                     const f32x4 g0 = *(const f32x4*)(gate + col), g1 = *(const f32x4*)(gate + col + 4);
;                     const size_t zo = (size_t)(r0 + ai * 128 + m * 16) * D + col; float* zp = zb + zo; const float* zq = zs + zo;
;                     f32x4 z0 = *(const f32x4*)zq, z1 = *(const f32x4*)(zq + 4);
;                     z0 += g0 * acc[ai][bj][m][0]; z1 += g1 * acc[ai][bj][m][1];
;                     *(f32x4*)zp = z0; *(f32x4*)(zp + 4) = z1;
.LBB0_795:
	s_ashr_i32 s29, s28, 31
	s_lshl_b64 s[28:29], s[28:29], 12
	s_add_u32 s28, s2, s28
	s_addc_u32 s29, s3, s29
	s_ashr_i32 s37, s36, 31
	s_lshl_b64 s[2:3], s[36:37], 12
	s_add_u32 s34, s34, s2
	s_addc_u32 s35, s35, s3
	s_add_i32 s2, s19, s66
	s_mul_i32 s2, s2, 6
	s_ashr_i32 s3, s2, 31
	s_lshl_b64 s[2:3], s[2:3], 12
	v_lshl_or_b32 v164, s70, 8, v166
	s_add_u32 s2, s67, s2
	v_ashrrev_i32_e32 v165, 31, v164
	s_addc_u32 s3, s68, s3
	v_lshlrev_b32_e32 v162, 2, v164
	global_load_dwordx4 v[198:201], v162, s[2:3]
	global_load_dwordx4 v[202:205], v162, s[2:3] offset:16
	global_load_dwordx4 v[206:209], v162, s[2:3] offset:512
	global_load_dwordx4 v[210:213], v162, s[2:3] offset:528
	v_add_lshl_u32 v163, v136, v164, 2
	global_load_dwordx4 v[214:217], v163, s[34:35]
	global_load_dwordx4 v[218:221], v163, s[34:35] offset:16
	global_load_dwordx4 v[222:225], v163, s[34:35] offset:512
	global_load_dwordx4 v[226:229], v163, s[34:35] offset:528
	v_add_lshl_u32 v180, v144, v164, 2
	global_load_dwordx4 v[230:233], v180, s[34:35]
	global_load_dwordx4 v[188:191], v180, s[34:35] offset:16
	global_load_dwordx4 v[192:195], v180, s[34:35] offset:512
	global_load_dwordx4 v[140:143], v180, s[34:35] offset:528
	v_add_lshl_u32 v181, v146, v164, 2
	global_load_dwordx4 v[168:171], v181, s[34:35]
	global_load_dwordx4 v[172:175], v181, s[34:35] offset:16
	global_load_dwordx4 v[176:179], v181, s[34:35] offset:512
	global_load_dwordx4 v[244:247], v181, s[34:35] offset:528
	s_waitcnt vmcnt(10)
	v_pk_fma_f32 v[128:129], v[128:129], v[200:201], v[216:217]
	v_pk_fma_f32 v[126:127], v[126:127], v[198:199], v[214:215]
	v_pk_fma_f32 v[124:125], v[124:125], v[204:205], v[220:221]
	v_pk_fma_f32 v[122:123], v[122:123], v[202:203], v[218:219]
	global_store_dwordx4 v163, v[126:129], s[28:29]
	global_store_dwordx4 v163, v[122:125], s[28:29] offset:16
	v_add_lshl_u32 v234, v148, v164, 2
	global_load_dwordx4 v[214:217], v234, s[34:35]
	global_load_dwordx4 v[218:221], v234, s[34:35] offset:16
	s_waitcnt vmcnt(12)
	v_pk_fma_f32 v[120:121], v[120:121], v[208:209], v[224:225]
	v_pk_fma_f32 v[118:119], v[118:119], v[206:207], v[222:223]
	v_pk_fma_f32 v[116:117], v[116:117], v[212:213], v[228:229]
	v_pk_fma_f32 v[114:115], v[114:115], v[210:211], v[226:227]
	global_store_dwordx4 v163, v[118:121], s[28:29] offset:512
	global_store_dwordx4 v163, v[114:117], s[28:29] offset:528
	global_load_dwordx4 v[222:225], v234, s[34:35] offset:512
	global_load_dwordx4 v[226:229], v234, s[34:35] offset:528
	s_waitcnt vmcnt(14)
	v_pk_fma_f32 v[112:113], v[112:113], v[200:201], v[232:233]
	v_pk_fma_f32 v[110:111], v[110:111], v[198:199], v[230:231]
	v_pk_fma_f32 v[108:109], v[108:109], v[204:205], v[190:191]
	v_pk_fma_f32 v[106:107], v[106:107], v[202:203], v[188:189]
	global_store_dwordx4 v180, v[110:113], s[28:29]
	global_store_dwordx4 v180, v[106:109], s[28:29] offset:16
	v_add_lshl_u32 v163, v150, v164, 2
	global_load_dwordx4 v[230:233], v163, s[34:35]
	global_load_dwordx4 v[188:191], v163, s[34:35] offset:16
	s_waitcnt vmcnt(16)
	v_pk_fma_f32 v[104:105], v[104:105], v[208:209], v[194:195]
	v_pk_fma_f32 v[102:103], v[102:103], v[206:207], v[192:193]
	v_pk_fma_f32 v[100:101], v[100:101], v[212:213], v[142:143]
	v_pk_fma_f32 v[98:99], v[98:99], v[210:211], v[140:141]
	global_store_dwordx4 v180, v[102:105], s[28:29] offset:512
	global_store_dwordx4 v180, v[98:101], s[28:29] offset:528
	global_load_dwordx4 v[192:195], v163, s[34:35] offset:512
	global_load_dwordx4 v[140:143], v163, s[34:35] offset:528
	s_waitcnt vmcnt(18)
	v_pk_fma_f32 v[96:97], v[96:97], v[200:201], v[170:171]
	v_pk_fma_f32 v[94:95], v[94:95], v[198:199], v[168:169]
	v_pk_fma_f32 v[92:93], v[92:93], v[204:205], v[174:175]
	v_pk_fma_f32 v[90:91], v[90:91], v[202:203], v[172:173]
	global_store_dwordx4 v181, v[94:97], s[28:29]
	global_store_dwordx4 v181, v[90:93], s[28:29] offset:16
	v_add_lshl_u32 v180, v152, v164, 2
	global_load_dwordx4 v[168:171], v180, s[34:35]
	global_load_dwordx4 v[172:175], v180, s[34:35] offset:16
	s_waitcnt vmcnt(20)
	v_pk_fma_f32 v[88:89], v[88:89], v[208:209], v[178:179]
	v_pk_fma_f32 v[86:87], v[86:87], v[206:207], v[176:177]
	v_pk_fma_f32 v[84:85], v[84:85], v[212:213], v[246:247]
	v_pk_fma_f32 v[82:83], v[82:83], v[210:211], v[244:245]
	global_store_dwordx4 v181, v[86:89], s[28:29] offset:512
	global_store_dwordx4 v181, v[82:85], s[28:29] offset:528
	global_load_dwordx4 v[176:179], v180, s[34:35] offset:512
	global_load_dwordx4 v[244:247], v180, s[34:35] offset:528
	s_waitcnt vmcnt(20)
; #define PG8_BAR __builtin_amdgcn_s_barrier()
; template <class AF, class Epi>
; DI void gemm_phase(LAS unsigned char* lds, const AF& af, const bf16_t* Bt, int lda, int K, const StaticOrder& S, const Epi& E) {
;     ...
;         if (!has_next) break;
; #pragma unroll
;         for (int a = 0; a < 2; ++a)
; #pragma unroll
;             for (int b = 0; b < 2; ++b)
; #pragma unroll
;                 for (int m = 0; m < 4; ++m)
; #pragma unroll
;                     for (int n = 0; n < 2; ++n) acc[a][b][m][n] = (f32x4){0.f, 0.f, 0.f, 0.f};
;         cur = nxt; cA = nA; cB = nB; ++ui;
;         if (wr == 1) PG8_BAR;
;     DI void operator()(const f32x4 (&acc)[2][2][4][2], const Unit& u, int wr, int wc, int fr, int fq) const {
;     ...
;         for (int ai = 0; ai < 2; ++ai)
; #pragma unroll
;             for (int m = 0; m < 4; ++m)
; #pragma unroll
;                 for (int bj = 0; bj < 2; ++bj) {
;                     const int col = col0 + bj * 128;
;                     const f32x4 g0 = *(const f32x4*)(gate + col), g1 = *(const f32x4*)(gate + col + 4);
;                     const size_t zo = (size_t)(r0 + ai * 128 + m * 16) * D + col; float* zp = zb + zo; const float* zq = zs + zo;
;                     f32x4 z0 = *(const f32x4*)zq, z1 = *(const f32x4*)(zq + 4);
;                     z0 += g0 * acc[ai][bj][m][0]; z1 += g1 * acc[ai][bj][m][1];
;                     *(f32x4*)zp = z0; *(f32x4*)(zp + 4) = z1;
;                     __builtin_amdgcn_sched_barrier(0);
;                 }
	v_pk_fma_f32 v[80:81], v[80:81], v[200:201], v[216:217]
	v_pk_fma_f32 v[78:79], v[78:79], v[198:199], v[214:215]
	v_pk_fma_f32 v[76:77], v[76:77], v[204:205], v[220:221]
	v_pk_fma_f32 v[74:75], v[74:75], v[202:203], v[218:219]
	global_store_dwordx4 v234, v[78:81], s[28:29]
	global_store_dwordx4 v234, v[74:77], s[28:29] offset:16
	v_add_lshl_u32 v181, v154, v164, 2
	global_load_dwordx4 v[214:217], v181, s[34:35]
	global_load_dwordx4 v[218:221], v181, s[34:35] offset:16
	s_waitcnt vmcnt(20)
	v_pk_fma_f32 v[72:73], v[72:73], v[208:209], v[224:225]
	v_pk_fma_f32 v[70:71], v[70:71], v[206:207], v[222:223]
	v_pk_fma_f32 v[68:69], v[68:69], v[212:213], v[228:229]
	v_pk_fma_f32 v[66:67], v[66:67], v[210:211], v[226:227]
	global_store_dwordx4 v234, v[70:73], s[28:29] offset:512
	global_store_dwordx4 v234, v[66:69], s[28:29] offset:528
	global_load_dwordx4 v[222:225], v181, s[34:35] offset:512
	global_load_dwordx4 v[226:229], v181, s[34:35] offset:528
	s_waitcnt vmcnt(20)
	v_pk_fma_f32 v[64:65], v[64:65], v[200:201], v[232:233]
	v_pk_fma_f32 v[62:63], v[62:63], v[198:199], v[230:231]
	v_pk_fma_f32 v[60:61], v[60:61], v[204:205], v[190:191]
	v_pk_fma_f32 v[58:59], v[58:59], v[202:203], v[188:189]
	global_store_dwordx4 v163, v[62:65], s[28:29]
	global_store_dwordx4 v163, v[58:61], s[28:29] offset:16
	v_add_lshl_u32 v234, v156, v164, 2
	global_load_dwordx4 v[230:233], v234, s[34:35]
	global_load_dwordx4 v[188:191], v234, s[34:35] offset:16
	s_waitcnt vmcnt(20)
	v_pk_fma_f32 v[56:57], v[56:57], v[208:209], v[194:195]
	v_pk_fma_f32 v[54:55], v[54:55], v[206:207], v[192:193]
	v_pk_fma_f32 v[52:53], v[52:53], v[212:213], v[142:143]
	v_pk_fma_f32 v[50:51], v[50:51], v[210:211], v[140:141]
	global_store_dwordx4 v163, v[54:57], s[28:29] offset:512
	global_store_dwordx4 v163, v[50:53], s[28:29] offset:528
	global_load_dwordx4 v[192:195], v234, s[34:35] offset:512
	global_load_dwordx4 v[140:143], v234, s[34:35] offset:528
	s_waitcnt vmcnt(20)
	v_pk_fma_f32 v[48:49], v[48:49], v[200:201], v[170:171]
	v_pk_fma_f32 v[46:47], v[46:47], v[198:199], v[168:169]
	v_pk_fma_f32 v[44:45], v[44:45], v[204:205], v[174:175]
	v_pk_fma_f32 v[42:43], v[42:43], v[202:203], v[172:173]
	global_store_dwordx4 v180, v[46:49], s[28:29]
	global_store_dwordx4 v180, v[42:45], s[28:29] offset:16
	s_waitcnt vmcnt(18)
	v_pk_fma_f32 v[40:41], v[40:41], v[208:209], v[178:179]
	v_pk_fma_f32 v[38:39], v[38:39], v[206:207], v[176:177]
	v_pk_fma_f32 v[36:37], v[36:37], v[212:213], v[246:247]
	v_pk_fma_f32 v[34:35], v[34:35], v[210:211], v[244:245]
	global_store_dwordx4 v180, v[38:41], s[28:29] offset:512
	global_store_dwordx4 v180, v[34:37], s[28:29] offset:528
	s_waitcnt vmcnt(16)
	v_pk_fma_f32 v[32:33], v[32:33], v[200:201], v[216:217]
	v_pk_fma_f32 v[30:31], v[30:31], v[198:199], v[214:215]
	v_pk_fma_f32 v[28:29], v[28:29], v[204:205], v[220:221]
	v_pk_fma_f32 v[26:27], v[26:27], v[202:203], v[218:219]
	global_store_dwordx4 v181, v[30:33], s[28:29]
	global_store_dwordx4 v181, v[26:29], s[28:29] offset:16
	s_waitcnt vmcnt(14)
	v_pk_fma_f32 v[24:25], v[24:25], v[208:209], v[224:225]
	v_pk_fma_f32 v[22:23], v[22:23], v[206:207], v[222:223]
	v_pk_fma_f32 v[20:21], v[20:21], v[212:213], v[228:229]
	v_pk_fma_f32 v[18:19], v[18:19], v[210:211], v[226:227]
	global_store_dwordx4 v181, v[22:25], s[28:29] offset:512
	global_store_dwordx4 v181, v[18:21], s[28:29] offset:528
	s_waitcnt vmcnt(12)
	v_pk_fma_f32 v[16:17], v[16:17], v[200:201], v[232:233]
	v_pk_fma_f32 v[14:15], v[14:15], v[198:199], v[230:231]
	v_pk_fma_f32 v[12:13], v[12:13], v[204:205], v[190:191]
	v_pk_fma_f32 v[10:11], v[10:11], v[202:203], v[188:189]
	global_store_dwordx4 v234, v[14:17], s[28:29]
	global_store_dwordx4 v234, v[10:13], s[28:29] offset:16
	s_waitcnt vmcnt(10)
	v_pk_fma_f32 v[8:9], v[8:9], v[208:209], v[194:195]
	v_pk_fma_f32 v[6:7], v[6:7], v[206:207], v[192:193]
	v_pk_fma_f32 v[4:5], v[4:5], v[212:213], v[142:143]
	v_pk_fma_f32 v[2:3], v[2:3], v[210:211], v[140:141]
	global_store_dwordx4 v234, v[6:9], s[28:29] offset:512
	global_store_dwordx4 v234, v[2:5], s[28:29] offset:528
	s_andn2_b64 vcc, exec, s[6:7]
	s_mov_b64 s[2:3], -1
	s_cbranch_vccnz .LBB0_781
	s_andn2_b64 vcc, exec, s[14:15]
	s_cbranch_vccnz .LBB0_780
	s_barrier
	s_branch .LBB0_780
